# v63 + branch-free NSA window edge masks + branch-free NSA top-n compare/select + barrier waiters poll top generation + s_setprio flips removed
# speedup vs baseline: 1.0097x; 1.0087x over previous
.LBB0_943:
	s_or_b64 exec, exec, s[4:5]
	v_add_u32_e32 v0, 0xa804, v197
	v_add_u32_e32 v2, 0xc904, v197
	ds_read2_b32 v[0:1], v0 offset1:1
	ds_read2_b32 v[2:3], v2 offset1:1
	v_add_u32_e32 v5, 0xea04, v197
	v_add_u32_e32 v8, 0x6304, v198
	ds_read2_b32 v[6:7], v5 offset1:1
	ds_read2_b32 v[8:9], v8 offset1:1
	ds_read_b32 v10, v197 offset:59916
	ds_read_b32 v11, v198 offset:25356
	v_cmp_gt_u32_e32 vcc, s2, v196
	s_waitcnt lgkmcnt(4)
	v_add_f32_e32 v0, v0, v2
	s_waitcnt lgkmcnt(3)
	v_add_f32_e32 v0, v0, v6
	s_waitcnt lgkmcnt(2)
	v_add_f32_e32 v0, v0, v8
	v_cndmask_b32_e32 v5, -1.0, v0, vcc
	v_add_u32_e32 v0, 12, v197
	v_add_f32_e32 v2, v1, v3
	ds_read2st64_b32 v[0:1], v0 offset0:168 offset1:201
	v_add_f32_e32 v2, v2, v7
	v_add_f32_e32 v2, v2, v9
	v_cmp_ge_u32_e32 vcc, s2, v200
	s_waitcnt lgkmcnt(0)
	v_add_f32_e32 v0, v0, v1
	v_add_f32_e32 v0, v0, v10
	v_cndmask_b32_e32 v6, -1.0, v2, vcc
	v_add_f32_e32 v0, v0, v11
	v_cmp_ge_u32_e32 vcc, s2, v201
	s_nop 1
	v_cndmask_b32_e32 v7, -1.0, v0, vcc
	v_and_b32_e32 v0, 64, v211
	v_cmp_gt_f32_e32 vcc, v5, v4
	v_add_u32_e32 v3, 64, v0
	s_nop 0
	v_cndmask_b32_e32 v0, v4, v5, vcc
	v_cndmask_b32_e32 v1, v196, v199, vcc
	v_cmp_gt_f32_e32 vcc, v6, v0
	s_nop 1
	v_cndmask_b32_e32 v0, v0, v6, vcc
	v_cndmask_b32_e32 v9, v1, v200, vcc
	v_cmp_gt_f32_e32 vcc, v7, v0
	s_nop 1
	v_cndmask_b32_e32 v8, v0, v7, vcc
	v_xor_b32_e32 v0, 1, v211
	v_cmp_lt_i32_e64 s[14:15], v0, v3
	s_nop 1
	v_cndmask_b32_e64 v0, v211, v0, s[14:15]
	v_lshlrev_b32_e32 v1, 2, v0
	s_nop 1
	v_mov_b32_dpp v2, v8 quad_perm:[1,0,3,2] row_mask:0xf bank_mask:0xf
	v_cndmask_b32_e32 v0, v9, v201, vcc
	s_nop 1
	v_mov_b32_dpp v9, v0 quad_perm:[1,0,3,2] row_mask:0xf bank_mask:0xf
	s_waitcnt lgkmcnt(1)
	v_cmp_lt_f32_e64 s[4:5], v8, v2
	v_cmp_eq_f32_e32 vcc, v8, v2
	s_waitcnt lgkmcnt(0)
	v_cmp_lt_i32_e64 s[14:15], v9, v0
	s_and_b64 s[14:15], vcc, s[14:15]
	s_or_b64 s[4:5], s[4:5], s[14:15]
	v_cndmask_b32_e64 v8, v8, v2, s[4:5]
	v_cndmask_b32_e64 v0, v0, v9, s[4:5]
	v_xor_b32_e32 v2, 2, v211
	v_cmp_lt_i32_e32 vcc, v2, v3
	s_nop 1
	v_cndmask_b32_e32 v2, v211, v2, vcc
	v_lshlrev_b32_e32 v2, 2, v2
	s_nop 1
	v_mov_b32_dpp v10, v8 quad_perm:[2,3,0,1] row_mask:0xf bank_mask:0xf
	s_waitcnt lgkmcnt(1)
	s_nop 1
	v_mov_b32_dpp v9, v0 quad_perm:[2,3,0,1] row_mask:0xf bank_mask:0xf
	s_waitcnt lgkmcnt(1)
	v_cmp_lt_f32_e64 s[4:5], v8, v10
	v_cmp_eq_f32_e32 vcc, v8, v10
	s_waitcnt lgkmcnt(0)
	v_cmp_lt_i32_e64 s[14:15], v9, v0
	s_and_b64 s[14:15], vcc, s[14:15]
	s_or_b64 s[4:5], s[4:5], s[14:15]
	v_cndmask_b32_e64 v8, v8, v10, s[4:5]
	v_cndmask_b32_e64 v0, v0, v9, s[4:5]
	s_waitcnt lgkmcnt(0)
	v_xor_b32_e32 v9, 4, v211
	v_cmp_lt_i32_e32 vcc, v9, v3
	s_nop 1
	v_cndmask_b32_e32 v3, v211, v9, vcc
	v_lshlrev_b32_e32 v3, 2, v3
	s_nop 1
	v_mov_b32_dpp v241, v8 row_half_mirror row_mask:0xf bank_mask:0xf
	s_nop 1
	v_mov_b32_dpp v10, v241 quad_perm:[3,2,1,0] row_mask:0xf bank_mask:0xf
	s_nop 1
	v_mov_b32_dpp v241, v0 row_half_mirror row_mask:0xf bank_mask:0xf
	s_nop 1
	v_mov_b32_dpp v9, v241 quad_perm:[3,2,1,0] row_mask:0xf bank_mask:0xf
	s_waitcnt lgkmcnt(1)
	v_cmp_lt_f32_e64 s[4:5], v8, v10
	v_cmp_eq_f32_e32 vcc, v8, v10
	s_waitcnt lgkmcnt(0)
	v_cmp_lt_i32_e64 s[14:15], v9, v0
	s_and_b64 s[14:15], vcc, s[14:15]
	s_or_b64 s[4:5], s[4:5], s[14:15]
	v_cndmask_b32_e64 v0, v0, v9, s[4:5]
	v_cmp_ne_u32_e32 vcc, v196, v0
	s_nop 1
	v_cndmask_b32_e32 v8, -1.0, v4, vcc
	v_cmp_ne_u32_e32 vcc, v199, v0
	s_nop 1
	v_cndmask_b32_e32 v5, -1.0, v5, vcc
	v_cmp_ne_u32_e32 vcc, v200, v0
	s_nop 1
	v_cndmask_b32_e32 v6, -1.0, v6, vcc
	v_cmp_ne_u32_e32 vcc, v201, v0
	s_nop 1
	v_cndmask_b32_e32 v7, -1.0, v7, vcc
	v_cmp_gt_f32_e32 vcc, v5, v8
	s_nop 1
	v_cndmask_b32_e32 v4, v8, v5, vcc
	s_waitcnt lgkmcnt(0)
	v_cndmask_b32_e32 v9, v196, v199, vcc
	v_cmp_gt_f32_e32 vcc, v6, v4
	s_nop 1
	v_cndmask_b32_e32 v4, v4, v6, vcc
	v_cndmask_b32_e32 v11, v9, v200, vcc
	v_cmp_gt_f32_e32 vcc, v7, v4
	s_nop 1
	v_cndmask_b32_e32 v9, v4, v7, vcc
	s_nop 1
	v_mov_b32_dpp v10, v9 quad_perm:[1,0,3,2] row_mask:0xf bank_mask:0xf
	v_cndmask_b32_e32 v4, v11, v201, vcc
	s_nop 1
	v_mov_b32_dpp v11, v4 quad_perm:[1,0,3,2] row_mask:0xf bank_mask:0xf
	s_waitcnt lgkmcnt(1)
	v_cmp_lt_f32_e64 s[4:5], v9, v10
	v_cmp_eq_f32_e32 vcc, v9, v10
	s_waitcnt lgkmcnt(0)
	v_cmp_lt_i32_e64 s[14:15], v11, v4
	s_and_b64 s[14:15], vcc, s[14:15]
	s_or_b64 s[4:5], s[4:5], s[14:15]
	v_cndmask_b32_e64 v9, v9, v10, s[4:5]
	v_cndmask_b32_e64 v4, v4, v11, s[4:5]
	s_waitcnt lgkmcnt(0)
	s_nop 1
	v_mov_b32_dpp v11, v9 quad_perm:[2,3,0,1] row_mask:0xf bank_mask:0xf
	s_nop 1
	v_mov_b32_dpp v10, v4 quad_perm:[2,3,0,1] row_mask:0xf bank_mask:0xf
	s_waitcnt lgkmcnt(1)
	v_cmp_lt_f32_e64 s[4:5], v9, v11
	v_cmp_eq_f32_e32 vcc, v9, v11
	s_waitcnt lgkmcnt(0)
	v_cmp_lt_i32_e64 s[14:15], v10, v4
	s_and_b64 s[14:15], vcc, s[14:15]
	s_or_b64 s[4:5], s[4:5], s[14:15]
	v_cndmask_b32_e64 v9, v9, v11, s[4:5]
	v_cndmask_b32_e64 v4, v4, v10, s[4:5]
	s_nop 1
	v_mov_b32_dpp v241, v9 row_half_mirror row_mask:0xf bank_mask:0xf
	s_nop 1
	v_mov_b32_dpp v11, v241 quad_perm:[3,2,1,0] row_mask:0xf bank_mask:0xf
	s_waitcnt lgkmcnt(1)
	s_nop 1
	v_mov_b32_dpp v241, v4 row_half_mirror row_mask:0xf bank_mask:0xf
	s_nop 1
	v_mov_b32_dpp v10, v241 quad_perm:[3,2,1,0] row_mask:0xf bank_mask:0xf
	s_waitcnt lgkmcnt(1)
	v_cmp_lt_f32_e64 s[4:5], v9, v11
	v_cmp_eq_f32_e32 vcc, v9, v11
	s_waitcnt lgkmcnt(0)
	v_cmp_lt_i32_e64 s[14:15], v10, v4
	s_and_b64 s[14:15], vcc, s[14:15]
	s_or_b64 s[4:5], s[4:5], s[14:15]
	v_cndmask_b32_e64 v4, v4, v10, s[4:5]
	v_cmp_ne_u32_e32 vcc, v196, v4
	s_nop 1
	v_cndmask_b32_e32 v8, -1.0, v8, vcc
	v_cmp_ne_u32_e32 vcc, v199, v4
	s_nop 1
	v_cndmask_b32_e32 v9, -1.0, v5, vcc
	v_cmp_ne_u32_e32 vcc, v200, v4
	s_nop 1
	v_cndmask_b32_e32 v6, -1.0, v6, vcc
	v_cmp_ne_u32_e32 vcc, v201, v4
	s_nop 1
	v_cndmask_b32_e32 v7, -1.0, v7, vcc
	v_cmp_gt_f32_e32 vcc, v9, v8
	s_nop 1
	v_cndmask_b32_e32 v5, v8, v9, vcc
	s_waitcnt lgkmcnt(0)
	v_cndmask_b32_e32 v10, v196, v199, vcc
	v_cmp_gt_f32_e32 vcc, v6, v5
	s_nop 1
	v_cndmask_b32_e32 v5, v5, v6, vcc
	v_cndmask_b32_e32 v12, v10, v200, vcc
	v_cmp_gt_f32_e32 vcc, v7, v5
	s_nop 1
	v_cndmask_b32_e32 v10, v5, v7, vcc
	s_nop 1
	v_mov_b32_dpp v11, v10 quad_perm:[1,0,3,2] row_mask:0xf bank_mask:0xf
	v_cndmask_b32_e32 v5, v12, v201, vcc
	s_nop 1
	v_mov_b32_dpp v12, v5 quad_perm:[1,0,3,2] row_mask:0xf bank_mask:0xf
	s_waitcnt lgkmcnt(1)
	v_cmp_lt_f32_e64 s[4:5], v10, v11
	v_cmp_eq_f32_e32 vcc, v10, v11
	s_waitcnt lgkmcnt(0)
	v_cmp_lt_i32_e64 s[14:15], v12, v5
	s_and_b64 s[14:15], vcc, s[14:15]
	s_or_b64 s[4:5], s[4:5], s[14:15]
	v_cndmask_b32_e64 v10, v10, v11, s[4:5]
	v_cndmask_b32_e64 v5, v5, v12, s[4:5]
	s_waitcnt lgkmcnt(0)
	s_nop 1
	v_mov_b32_dpp v12, v10 quad_perm:[2,3,0,1] row_mask:0xf bank_mask:0xf
	s_nop 1
	v_mov_b32_dpp v11, v5 quad_perm:[2,3,0,1] row_mask:0xf bank_mask:0xf
	s_waitcnt lgkmcnt(1)
	v_cmp_lt_f32_e64 s[4:5], v10, v12
	v_cmp_eq_f32_e32 vcc, v10, v12
	s_waitcnt lgkmcnt(0)
	v_cmp_lt_i32_e64 s[14:15], v11, v5
	s_and_b64 s[14:15], vcc, s[14:15]
	s_or_b64 s[4:5], s[4:5], s[14:15]
	v_cndmask_b32_e64 v10, v10, v12, s[4:5]
	v_cndmask_b32_e64 v5, v5, v11, s[4:5]
	s_nop 1
	v_mov_b32_dpp v241, v10 row_half_mirror row_mask:0xf bank_mask:0xf
	s_nop 1
	v_mov_b32_dpp v12, v241 quad_perm:[3,2,1,0] row_mask:0xf bank_mask:0xf
	s_waitcnt lgkmcnt(1)
	s_nop 1
	v_mov_b32_dpp v241, v5 row_half_mirror row_mask:0xf bank_mask:0xf
	s_nop 1
	v_mov_b32_dpp v11, v241 quad_perm:[3,2,1,0] row_mask:0xf bank_mask:0xf
	s_waitcnt lgkmcnt(1)
	v_cmp_lt_f32_e64 s[4:5], v10, v12
	v_cmp_eq_f32_e32 vcc, v10, v12
	s_waitcnt lgkmcnt(0)
	v_cmp_lt_i32_e64 s[14:15], v11, v5
	s_and_b64 s[14:15], vcc, s[14:15]
	s_or_b64 s[4:5], s[4:5], s[14:15]
	v_cndmask_b32_e64 v5, v5, v11, s[4:5]
	v_cmp_ne_u32_e32 vcc, v196, v5
	s_nop 1
	v_cndmask_b32_e32 v8, -1.0, v8, vcc
	v_cmp_ne_u32_e32 vcc, v199, v5
	s_nop 1
	v_cndmask_b32_e32 v9, -1.0, v9, vcc
	v_cmp_ne_u32_e32 vcc, v200, v5
	s_nop 1
	v_cndmask_b32_e32 v10, -1.0, v6, vcc
	v_cmp_ne_u32_e32 vcc, v201, v5
	s_nop 1
	v_cndmask_b32_e32 v7, -1.0, v7, vcc
	v_cmp_gt_f32_e32 vcc, v9, v8
	s_nop 1
	v_cndmask_b32_e32 v6, v8, v9, vcc
	s_waitcnt lgkmcnt(0)
	v_cndmask_b32_e32 v11, v196, v199, vcc
	v_cmp_gt_f32_e32 vcc, v10, v6
	s_nop 1
	v_cndmask_b32_e32 v6, v6, v10, vcc
	v_cndmask_b32_e32 v13, v11, v200, vcc
	v_cmp_gt_f32_e32 vcc, v7, v6
	s_nop 1
	v_cndmask_b32_e32 v11, v6, v7, vcc
	s_nop 1
	v_mov_b32_dpp v12, v11 quad_perm:[1,0,3,2] row_mask:0xf bank_mask:0xf
	v_cndmask_b32_e32 v6, v13, v201, vcc
	s_nop 1
	v_mov_b32_dpp v13, v6 quad_perm:[1,0,3,2] row_mask:0xf bank_mask:0xf
	s_waitcnt lgkmcnt(1)
	v_cmp_lt_f32_e64 s[4:5], v11, v12
	v_cmp_eq_f32_e32 vcc, v11, v12
	s_waitcnt lgkmcnt(0)
	v_cmp_lt_i32_e64 s[14:15], v13, v6
	s_and_b64 s[14:15], vcc, s[14:15]
	s_or_b64 s[4:5], s[4:5], s[14:15]
	v_cndmask_b32_e64 v11, v11, v12, s[4:5]
	v_cndmask_b32_e64 v6, v6, v13, s[4:5]
	s_waitcnt lgkmcnt(0)
	s_nop 1
	v_mov_b32_dpp v13, v11 quad_perm:[2,3,0,1] row_mask:0xf bank_mask:0xf
	s_nop 1
	v_mov_b32_dpp v12, v6 quad_perm:[2,3,0,1] row_mask:0xf bank_mask:0xf
	s_waitcnt lgkmcnt(1)
	v_cmp_lt_f32_e64 s[4:5], v11, v13
	v_cmp_eq_f32_e32 vcc, v11, v13
	s_waitcnt lgkmcnt(0)
	v_cmp_lt_i32_e64 s[14:15], v12, v6
	s_and_b64 s[14:15], vcc, s[14:15]
	s_or_b64 s[4:5], s[4:5], s[14:15]
	v_cndmask_b32_e64 v11, v11, v13, s[4:5]
	v_cndmask_b32_e64 v6, v6, v12, s[4:5]
	s_nop 1
	v_mov_b32_dpp v241, v11 row_half_mirror row_mask:0xf bank_mask:0xf
	s_nop 1
	v_mov_b32_dpp v13, v241 quad_perm:[3,2,1,0] row_mask:0xf bank_mask:0xf
	s_waitcnt lgkmcnt(1)
	s_nop 1
	v_mov_b32_dpp v241, v6 row_half_mirror row_mask:0xf bank_mask:0xf
	s_nop 1
	v_mov_b32_dpp v12, v241 quad_perm:[3,2,1,0] row_mask:0xf bank_mask:0xf
	s_waitcnt lgkmcnt(1)
	v_cmp_lt_f32_e64 s[4:5], v11, v13
	v_cmp_eq_f32_e32 vcc, v11, v13
	s_waitcnt lgkmcnt(0)
	v_cmp_lt_i32_e64 s[14:15], v12, v6
	s_and_b64 s[14:15], vcc, s[14:15]
	s_or_b64 s[4:5], s[4:5], s[14:15]
	v_cndmask_b32_e64 v6, v6, v12, s[4:5]
	v_cmp_ne_u32_e32 vcc, v196, v6
	s_nop 1
	v_cndmask_b32_e32 v8, -1.0, v8, vcc
	v_cmp_ne_u32_e32 vcc, v199, v6
	s_nop 1
	v_cndmask_b32_e32 v9, -1.0, v9, vcc
	v_cmp_ne_u32_e32 vcc, v200, v6
	s_nop 1
	v_cndmask_b32_e32 v10, -1.0, v10, vcc
	v_cmp_ne_u32_e32 vcc, v201, v6
	s_nop 1
	v_cndmask_b32_e32 v7, -1.0, v7, vcc
	v_cmp_gt_f32_e32 vcc, v9, v8
	s_nop 1
	v_cndmask_b32_e32 v8, v8, v9, vcc
	v_cndmask_b32_e32 v9, v196, v199, vcc
	v_cmp_gt_f32_e32 vcc, v10, v8
	s_nop 1
	v_cndmask_b32_e32 v8, v8, v10, vcc
	v_cndmask_b32_e32 v10, v9, v200, vcc
	v_cmp_gt_f32_e32 vcc, v7, v8
	s_nop 1
	v_cndmask_b32_e32 v8, v8, v7, vcc
	s_nop 1
	v_mov_b32_dpp v9, v8 quad_perm:[1,0,3,2] row_mask:0xf bank_mask:0xf
	v_cndmask_b32_e32 v7, v10, v201, vcc
	s_nop 1
	v_mov_b32_dpp v1, v7 quad_perm:[1,0,3,2] row_mask:0xf bank_mask:0xf
	s_waitcnt lgkmcnt(1)
	v_cmp_lt_f32_e64 s[4:5], v8, v9
	v_cmp_eq_f32_e32 vcc, v8, v9
	s_waitcnt lgkmcnt(0)
	v_cmp_lt_i32_e64 s[14:15], v1, v7
	s_and_b64 s[14:15], vcc, s[14:15]
	s_or_b64 s[4:5], s[4:5], s[14:15]
	v_cndmask_b32_e64 v8, v8, v9, s[4:5]
	v_cndmask_b32_e64 v7, v7, v1, s[4:5]
	s_nop 1
	v_mov_b32_dpp v9, v8 quad_perm:[2,3,0,1] row_mask:0xf bank_mask:0xf
	s_waitcnt lgkmcnt(1)
	s_nop 1
	v_mov_b32_dpp v1, v7 quad_perm:[2,3,0,1] row_mask:0xf bank_mask:0xf
	s_waitcnt lgkmcnt(1)
	v_cmp_lt_f32_e64 s[4:5], v8, v9
	v_cmp_eq_f32_e32 vcc, v8, v9
	s_waitcnt lgkmcnt(0)
	v_cmp_lt_i32_e64 s[14:15], v1, v7
	s_and_b64 s[14:15], vcc, s[14:15]
	s_or_b64 s[4:5], s[4:5], s[14:15]
	v_cndmask_b32_e64 v8, v8, v9, s[4:5]
	v_cndmask_b32_e64 v7, v7, v1, s[4:5]
	s_nop 1
	v_mov_b32_dpp v241, v8 row_half_mirror row_mask:0xf bank_mask:0xf
	s_nop 1
	v_mov_b32_dpp v2, v241 quad_perm:[3,2,1,0] row_mask:0xf bank_mask:0xf
	s_waitcnt lgkmcnt(1)
	s_nop 1
	v_mov_b32_dpp v241, v7 row_half_mirror row_mask:0xf bank_mask:0xf
	s_nop 1
	v_mov_b32_dpp v1, v241 quad_perm:[3,2,1,0] row_mask:0xf bank_mask:0xf
	s_waitcnt lgkmcnt(1)
	v_cmp_lt_f32_e64 s[4:5], v8, v2
	v_cmp_eq_f32_e32 vcc, v8, v2
	s_waitcnt lgkmcnt(0)
	v_cmp_lt_i32_e64 s[14:15], v1, v7
	s_and_b64 s[14:15], vcc, s[14:15]
	s_or_b64 s[4:5], s[4:5], s[14:15]
	v_cndmask_b32_e64 v7, v7, v1, s[4:5]
	s_add_i32 s3, s93, -1
	s_lshl_b32 s2, 1, s93
	s_lshl_b32 s3, 1, s3
	v_lshlrev_b32_e64 v3, v4, 1
	v_lshlrev_b32_e64 v0, v0, 1
	s_or_b32 s2, s2, s3
	s_waitcnt lgkmcnt(0)
	v_lshlrev_b32_e64 v1, v6, 1
	v_lshlrev_b32_e64 v2, v5, 1
	v_or3_b32 v0, s2, v0, v3
	v_lshlrev_b32_e64 v4, v7, 1
	v_or3_b32 v0, v0, v2, v1
	v_or3_b32 v0, v0, v4, 1
	s_mov_b64 s[4:5], 0
